# attention: one static s_setprio 1 for waves 4-7 per unit
# baseline (speedup 1.0000x reference)
; template <int VARI>
; __device__ __forceinline__ void attention_phase(ArgsP a, int l, LAS unsigned char* lds, int cslot) {
;     ...
;     for (;;) {
;         if (tid == 0) *slot = atomicAdd(counter, 1);
;         __syncthreads();
;         const int idx = *slot;
;         __syncthreads();
.LBB0_563:
	s_setprio 0
	s_waitcnt lgkmcnt(0)
	s_barrier

; #define LAS __attribute__((address_space(3)))
; template <int MODE, int VARI>
; __device__ __forceinline__ void attn_unit(LAS unsigned char* lds, const int tid, const AttnP& a, float c2, float lam, const float* subln, float outscale, float fox_u, const bool fast) {
;     ...
;     const int wid = __builtin_amdgcn_readfirstlane(tid >> 6), lane = tid & 63, r32 = lane & 31, hi = lane >> 5, grp = wid >> 2;
;     const int wrow = (WIDE ? wid : (wid & 3)) * 32, kcoff = MODE == 0 ? grp * 64 : 0, khalf = SPLIT ? grp : 0;
;     const int NT = (a.P0 + (WIDE ? 256 : 128)) >> 6;
;     const int qpos0 = a.P0 + wrow, pos = qpos0 + r32;
;     LAS unsigned char* V_lds = lds; LAS unsigned char* K_lds = lds + OFF_K; LAS float* B_lds = (LAS float*)(lds + OFF_B);
;     LAS float* wsc = (LAS float*)(lds + OFF_W) + wid * 64; LAS float* li_l = wsc; LAS float* al_l = wsc + 32;
;     bf16x8 qr[DK / 16];
;     { const bf16_t* qp = a.Q + (size_t)pos * a.qpitch + kcoff + hi * 8;
; #pragma unroll
;       for (int d0 = 0; d0 < DK / 16; ++d0) qr[d0] = *(const bf16x8*)(qp + d0 * 16); }
;     ...
;       unsigned voff[2], koff[KW / 64], kstp[KW / 64], boff = 0; int vt = t_lo, kt = t_lo;
;       { int tt_ = tid; asm volatile("" : "+v"(tt_)); const int ln_ = tt_ & 63;
; #pragma unroll
;         for (int i_ = 0; i_ < 2; ++i_) { const int ch_ = wid + 8 * i_, b_ = ch_ * 1024 + ln_ * 16, sub_ = b_ >> 9, wi_ = (b_ & 511) >> 1;
;             const int kk_ = (sub_ >> 2) * 8 + (wi_ >> 5), c_ = (sub_ & 3) * 32 + (wi_ & 31), k_ = (kk_ & ~0xC) | ((kk_ & 4) << 1) | ((kk_ & 8) >> 1);
;             voff[i_] = (unsigned)(((t_lo * 64 + k_) * a.vpitch + c_) * 2); }
; #pragma unroll
;         for (int i_ = 0; i_ < KW / 64; ++i_) { const int ch_ = wid + 8 * i_, b_ = ch_ * 1024 + ln_ * 16, krow_ = b_ / (KW * 2), cs_ = (b_ % (KW * 2)) >> 4;
;             const int kcc_ = cs_ ^ (kswz<KW>(krow_) >> 4);
;             if (MODE == 2 && kcc_ >= 8) { koff[i_] = (unsigned)((const char*)a.K1 - (const char*)a.K0) + (unsigned)(((t_lo * 64 + krow_) * a.k1pitch + (kcc_ - 8) * 8) * 2); kstp[i_] = (unsigned)(64 * a.k1pitch * 2); }
;             else { koff[i_] = (unsigned)(((t_lo * 64 + krow_) * a.k0pitch + kcc_ * 8) * 2); kstp[i_] = (unsigned)(64 * a.k0pitch * 2); } }
;         if (MODE == 1) boff = (unsigned)((t_lo * 64 + ln_) * 32); }
.Lafter_table:
	s_movk_i32 s2, 0xff
	v_mov_b32_e32 v230, v205
	v_readfirstlane_b32 s6, v205
	s_nop 3
	s_lshr_b32 s6, s6, 8
	s_cmp_eq_u32 s6, 0
	s_cbranch_scc1 .Lprio_skip
	s_setprio 1
.Lprio_skip:
	s_waitcnt vmcnt(0)
	v_cmp_lt_i32_e32 vcc, s2, v0
	v_readfirstlane_b32 s10, v0
	s_cbranch_vccz .LBB0_802
	s_cmpk_gt_u32 s10, 0x1bf
	s_cbranch_scc0 .LBB0_766
	s_add_i32 s2, s10, 0xfffffe40
	s_lshr_b32 s11, s2, 5
	s_mul_i32 s36, s11, 0xc0
	s_lshl_b64 s[6:7], s[36:37], 1
	s_add_u32 s12, s52, s6
	s_addc_u32 s13, s53, s7
	s_lshl_b32 s2, s11, 9
	v_readlane_b32 s6, v255, 7
	v_readlane_b32 s7, v255, 8
	s_add_u32 s60, s6, s2
	s_addc_u32 s61, s7, 0
	s_lshl_b32 s2, s10, 8
	s_and_b32 s7, s2, 0x1f00
	v_readfirstlane_b32 s2, v230
	s_ashr_i32 s8, s2, 6
	s_lshl_b32 s6, s8, 5
	v_and_b32_e32 v231, 31, v230
	s_add_i32 s76, s6, s7
	v_bfe_u32 v232, v230, 5, 1
	v_or_b32_e32 v0, s76, v231
	v_mov_b64_e32 v[2:3], s[12:13]
	v_mad_i64_i32 v[2:3], s[12:13], v0, s3, v[2:3]
	v_lshlrev_b32_e32 v212, 4, v232
	v_mov_b32_e32 v213, v1
	v_lshl_add_u64 v[2:3], v[2:3], 0, v[212:213]
	global_load_dwordx4 v[144:147], v[2:3], off
	global_load_dwordx4 v[148:151], v[2:3], off offset:32
	global_load_dwordx4 v[152:155], v[2:3], off offset:64
	global_load_dwordx4 v[156:159], v[2:3], off offset:96
	global_load_dwordx4 v[160:163], v[2:3], off offset:128
	global_load_dwordx4 v[164:167], v[2:3], off offset:160
	global_load_dwordx4 v[168:171], v[2:3], off offset:192
	global_load_dwordx4 v[172:175], v[2:3], off offset:224
	global_load_dwordx4 v[176:179], v[2:3], off offset:256
	global_load_dwordx4 v[180:183], v[2:3], off offset:288
	global_load_dwordx4 v[184:187], v[2:3], off offset:320
	global_load_dwordx4 v[188:191], v[2:3], off offset:352
	s_and_b32 s2, s2, 0x3fffffc0
	s_lshl_b32 s2, s2, 2
	v_readlane_b32 s14, v255, 17
	s_add_i32 s9, s7, 0x100
	s_add_i32 s26, s2, 0x100
	v_readlane_b32 s15, v255, 18
	v_and_b32_e32 v213, 63, v230
	s_add_i32 s26, s26, 0x1f800
	s_lshr_b32 s59, s9, 6
	s_mov_b64 s[12:13], -1
	s_and_b64 vcc, exec, s[14:15]
	s_cbranch_vccz .LBB0_609
	s_lshl_b32 s18, s8, 10
	v_mov_b32_e32 v6, v213
	v_mov_b32_e32 v0, v230
	s_ashr_i32 s2, s18, 8
	s_and_b32 s14, s2, -16
	v_lshlrev_b32_e32 v2, 4, v0
	s_lshr_b32 s2, s2, 1
	v_and_b32_e32 v2, 0x200, v2
	v_lshlrev_b32_e32 v3, 3, v0
	v_bfe_u32 v4, v0, 2, 2
	v_lshrrev_b32_e32 v0, 1, v0
	s_and_b32 s15, s2, 4
	v_or_b32_e32 v2, s18, v2
	v_and_or_b32 v4, v0, 8, v4
	s_or_b32 s2, s15, s14
	v_lshrrev_b32_e32 v2, 4, v2
	v_and_b32_e32 v3, 24, v3
	v_or_b32_e32 v0, s2, v4
	s_add_i32 s27, s18, 0x2000
	v_and_or_b32 v5, v2, s93, v3
	v_mul_hi_i32_i24_e32 v3, 0xc00, v0
	v_mul_i32_i24_e32 v2, 0xc00, v0
	s_ashr_i32 s12, s27, 8
	v_lshl_add_u64 v[2:3], s[60:61], 0, v[2:3]
	v_lshlrev_b32_e32 v0, 1, v5
	s_and_b32 s2, s12, -16
	s_lshr_b32 s12, s12, 1
	v_lshl_add_u64 v[2:3], v[2:3], 0, v[0:1]
	s_add_i32 s19, s18, 0x100
	s_and_b32 s38, s12, 4
	v_lshl_add_u64 v[2:3], v[2:3], 0, s[96:97]
	s_mov_b32 m0, s19
	s_or_b32 s12, s38, s2
	global_load_lds_dwordx4 v[2:3], off
	v_or_b32_e32 v2, s12, v4
	v_mul_hi_i32_i24_e32 v3, 0xc00, v2
	v_mul_i32_i24_e32 v2, 0xc00, v2
	v_lshl_add_u64 v[2:3], s[60:61], 0, v[2:3]
	v_lshl_add_u64 v[2:3], v[2:3], 0, v[0:1]
	v_lshl_add_u64 v[2:3], v[2:3], 0, s[96:97]
	s_add_i32 m0, s19, 0x2000
	v_mov_b32_e32 v0, v230
	global_load_lds_dwordx4 v[2:3], off
	s_nop 0
	v_lshlrev_b32_e32 v0, 4, v0
	v_and_b32_e32 v7, 0x3f0, v0
	v_or_b32_e32 v0, s18, v7
	v_mul_hi_i32 v2, v0, s79
	v_lshrrev_b32_e32 v3, 31, v2
	v_ashrrev_i32_e32 v2, 6, v2
	v_add_u32_e32 v4, v2, v3
	v_mul_i32_i24_e32 v2, 0x180, v4
	v_sub_u32_e32 v0, v0, v2
	v_lshrrev_b32_e32 v3, 2, v4
	v_ashrrev_i32_e32 v0, 4, v0
	v_bfe_u32 v2, v4, 1, 2
	v_and_b32_e32 v3, 4, v3
	v_bitop3_b32 v0, v2, v0, v3 bitop3:0x36
	v_cmp_gt_i32_e32 vcc, 8, v0
	v_lshlrev_b32_e32 v0, 3, v0
	s_and_saveexec_b64 s[12:13], vcc
	s_xor_b64 s[12:13], exec, s[12:13]
	v_mul_hi_i32_i24_e32 v3, 0x2600, v4
	v_mul_i32_i24_e32 v2, 0x2600, v4
	v_lshl_add_u64 v[2:3], s[72:73], 0, v[2:3]
	v_ashrrev_i32_e32 v5, 31, v0
	v_mov_b32_e32 v4, v0
	v_lshl_add_u64 v[2:3], v[4:5], 1, v[2:3]
	s_andn2_saveexec_b64 s[12:13], s[12:13]
	v_mul_hi_i32_i24_e32 v3, 0xc00, v4
	v_mul_i32_i24_e32 v2, 0xc00, v4
	v_lshl_add_u64 v[2:3], s[60:61], 0, v[2:3]
	s_movk_i32 s34, 0xff80
	v_lshl_add_u64 v[2:3], v[0:1], 1, v[2:3]
	s_mov_b32 s35, -1
	v_lshl_add_u64 v[2:3], v[2:3], 0, s[34:35]
	s_or_b64 exec, exec, s[12:13]
	s_add_i32 m0, s19, 0xc000
	s_nop 0
	global_load_lds_dwordx4 v[2:3], off
	v_or_b32_e32 v2, s27, v7
	v_mul_hi_i32 v0, v2, s79
	v_lshrrev_b32_e32 v3, 31, v0
	v_ashrrev_i32_e32 v0, 6, v0
	v_add_u32_e32 v0, v0, v3
	v_mul_i32_i24_e32 v3, 0x180, v0
	v_sub_u32_e32 v2, v2, v3
	v_lshrrev_b32_e32 v4, 2, v0
	v_ashrrev_i32_e32 v2, 4, v2
	v_bfe_u32 v3, v0, 1, 2
	v_and_b32_e32 v4, 4, v4
	v_bitop3_b32 v2, v3, v2, v4 bitop3:0x36
	v_cmp_gt_i32_e32 vcc, 8, v2
	v_lshlrev_b32_e32 v2, 3, v2
; #define LAS __attribute__((address_space(3)))
; template <int MODE, int VARI>
; __device__ __forceinline__ void attn_unit(LAS unsigned char* lds, const int tid, const AttnP& a, float c2, float lam, const float* subln, float outscale, float fox_u, const bool fast) {
;     ...
;     float m_reg = -1e30f, l_reg = 0.f; f32x16 o[4];
; #pragma unroll
;     for (int d = 0; d < 4; ++d)
; #pragma unroll
;         for (int r = 0; r < 16; ++r) o[d][r] = 0.f;
;     ...
;       unsigned voff[2], koff[KW / 64], kstp[KW / 64], boff = 0; int vt = t_lo, kt = t_lo;
;       { int tt_ = tid; asm volatile("" : "+v"(tt_)); const int ln_ = tt_ & 63;
; #pragma unroll
;         for (int i_ = 0; i_ < 2; ++i_) { const int ch_ = wid + 8 * i_, b_ = ch_ * 1024 + ln_ * 16, sub_ = b_ >> 9, wi_ = (b_ & 511) >> 1;
;             const int kk_ = (sub_ >> 2) * 8 + (wi_ >> 5), c_ = (sub_ & 3) * 32 + (wi_ & 31), k_ = (kk_ & ~0xC) | ((kk_ & 4) << 1) | ((kk_ & 8) >> 1);
;             voff[i_] = (unsigned)(((t_lo * 64 + k_) * a.vpitch + c_) * 2); }
; #pragma unroll
;         for (int i_ = 0; i_ < KW / 64; ++i_) { const int ch_ = wid + 8 * i_, b_ = ch_ * 1024 + ln_ * 16, krow_ = b_ / (KW * 2), cs_ = (b_ % (KW * 2)) >> 4;
;             const int kcc_ = cs_ ^ (kswz<KW>(krow_) >> 4);
;             if (MODE == 2 && kcc_ >= 8) { koff[i_] = (unsigned)((const char*)a.K1 - (const char*)a.K0) + (unsigned)(((t_lo * 64 + krow_) * a.k1pitch + (kcc_ - 8) * 8) * 2); kstp[i_] = (unsigned)(64 * a.k1pitch * 2); }
;             else { koff[i_] = (unsigned)(((t_lo * 64 + krow_) * a.k0pitch + kcc_ * 8) * 2); kstp[i_] = (unsigned)(64 * a.k0pitch * 2); } }
;         if (MODE == 1) boff = (unsigned)((t_lo * 64 + ln_) * 32); }
;     ...
;       LAS float* Bw_lds = B_lds + wid * 192;
;       const float ctp = ct2 + cP0;
;       int i0 = t_lo % 3, i1 = (t_lo + 1) % 3, i2 = (t_lo + 2) % 3;
;       DMA_K(t_lo, i0); DMA_V(t_lo, i0); DMA_K(t_lo + 1, i1); DMA_V(t_lo + 1, i1); DMA_K(t_lo + 2, i2);
;       asm volatile("s_waitcnt vmcnt(0)" ::: "memory"); __builtin_amdgcn_s_barrier(); asm volatile("" ::: "memory");
;       f32x16 pA0, pA1;
;       QK_TILE(pA0, pA1, i0);
;       asm volatile("s_waitcnt lgkmcnt(0)" ::: "memory"); __builtin_amdgcn_s_barrier(); asm volatile("" ::: "memory");
	s_and_saveexec_b64 s[12:13], vcc
	s_xor_b64 s[12:13], exec, s[12:13]
	v_mul_hi_i32_i24_e32 v5, 0x2600, v0
	v_mul_i32_i24_e32 v4, 0x2600, v0
	v_lshl_add_u64 v[4:5], s[72:73], 0, v[4:5]
	v_ashrrev_i32_e32 v3, 31, v2
	v_lshl_add_u64 v[4:5], v[2:3], 1, v[4:5]
	s_andn2_saveexec_b64 s[12:13], s[12:13]
	v_mul_hi_i32_i24_e32 v5, 0xc00, v0
	v_mul_i32_i24_e32 v4, 0xc00, v0
	v_lshl_add_u64 v[4:5], s[60:61], 0, v[4:5]
	v_mov_b32_e32 v3, v1
	s_movk_i32 s34, 0xff80
	v_lshl_add_u64 v[2:3], v[2:3], 1, v[4:5]
	s_mov_b32 s35, -1
	v_lshl_add_u64 v[4:5], v[2:3], 0, s[34:35]
	s_or_b64 exec, exec, s[12:13]
	s_add_i32 m0, s19, 0xe000
	s_add_i32 s36, s18, 0x4000
	global_load_lds_dwordx4 v[4:5], off
	v_or_b32_e32 v2, s36, v7
	v_mul_hi_i32 v0, v2, s79
	v_lshrrev_b32_e32 v3, 31, v0
	v_ashrrev_i32_e32 v0, 6, v0
	v_add_u32_e32 v0, v0, v3
	v_mul_i32_i24_e32 v3, 0x180, v0
	v_sub_u32_e32 v2, v2, v3
	v_lshrrev_b32_e32 v4, 2, v0
	v_ashrrev_i32_e32 v2, 4, v2
	v_bfe_u32 v3, v0, 1, 2
	v_and_b32_e32 v4, 4, v4
	v_bitop3_b32 v2, v3, v2, v4 bitop3:0x36
	v_cmp_gt_i32_e32 vcc, 8, v2
	v_lshlrev_b32_e32 v4, 3, v2
	s_and_saveexec_b64 s[12:13], vcc
	s_xor_b64 s[12:13], exec, s[12:13]
	v_mul_hi_i32_i24_e32 v3, 0x2600, v0
	v_mul_i32_i24_e32 v2, 0x2600, v0
	v_lshl_add_u64 v[2:3], s[72:73], 0, v[2:3]
	v_ashrrev_i32_e32 v5, 31, v4
	v_lshl_add_u64 v[2:3], v[4:5], 1, v[2:3]
	s_andn2_saveexec_b64 s[12:13], s[12:13]
	v_mul_hi_i32_i24_e32 v3, 0xc00, v0
	v_mul_i32_i24_e32 v2, 0xc00, v0
	v_lshl_add_u64 v[2:3], s[60:61], 0, v[2:3]
	v_mov_b32_e32 v5, v1
	s_movk_i32 s34, 0xff80
	v_lshl_add_u64 v[2:3], v[4:5], 1, v[2:3]
	s_mov_b32 s35, -1
	v_lshl_add_u64 v[2:3], v[2:3], 0, s[34:35]
	s_or_b64 exec, exec, s[12:13]
	s_add_i32 s12, s78, 0x100
	s_add_i32 m0, s12, s36
	v_lshrrev_b32_e32 v4, 2, v6
	global_load_lds_dwordx4 v[2:3], off
	v_ashrrev_i32_e32 v2, 5, v6
	v_lshrrev_b32_e32 v3, 1, v6
	v_and_b32_e32 v4, 4, v4
	v_and_b32_e32 v0, 31, v6
	v_and_or_b32 v3, v3, 3, v4
	v_lshlrev_b32_e32 v112, 4, v2
	v_mov_b32_e32 v7, s12
	s_movk_i32 s12, 0x180
	v_lshlrev_b32_e32 v4, 4, v6
	v_lshlrev_b32_e32 v5, 1, v6
	v_lshlrev_b32_e32 v3, 4, v3
	v_mad_u32_u24 v113, v0, s12, v7
	v_lshlrev_b32_e32 v7, 3, v6
	v_cmp_gt_u32_e64 s[12:13], 32, v6
	v_add_u32_e32 v6, 32, v112
	v_xor_b32_e32 v116, v3, v6
	v_add_u32_e32 v6, 64, v112
	v_xor_b32_e32 v117, v3, v6
	v_add_u32_e32 v6, 0x60, v112
	v_xor_b32_e32 v118, v3, v6
	v_add_u32_e32 v6, 0x80, v112
	v_xor_b32_e32 v119, v3, v6
	v_add_u32_e32 v6, 0xa0, v112
	v_xor_b32_e32 v120, v3, v6
	v_add_u32_e32 v6, 0xc0, v112
	v_xor_b32_e32 v121, v3, v6
	v_add_u32_e32 v6, 0xe0, v112
	v_xor_b32_e32 v122, v3, v6
	v_add_u32_e32 v6, 0x100, v112
	v_xor_b32_e32 v123, v3, v6
	v_add_u32_e32 v6, 0x120, v112
	v_xor_b32_e32 v124, v3, v6
	v_add_u32_e32 v6, 0x140, v112
	v_and_b32_e32 v5, 32, v5
	v_xor_b32_e32 v125, v3, v6
	v_add_u32_e32 v6, 0x160, v112
	s_movk_i32 s33, 0x118
	v_and_b32_e32 v4, 0xc0, v4
	v_lshlrev_b32_e32 v2, 2, v2
	v_lshl_add_u32 v114, v0, 2, s26
	v_xor_b32_e32 v115, v3, v112
	v_xor_b32_e32 v126, v3, v6
	v_and_or_b32 v3, v7, s33, v5
	s_movk_i32 s33, 0x100
	v_add_u32_e32 v0, s6, v0
	v_mov_b32_e32 v14, v1
	v_mov_b32_e32 v15, v1
	v_add3_u32 v127, v4, s33, v3
	v_sub_u32_e32 v128, v0, v2
	s_add_i32 s35, s14, s15
	s_add_i32 s38, s2, s38
	v_mov_b32_e32 v0, v1
	v_mov_b32_e32 v2, v1
	v_mov_b32_e32 v3, v1
	v_mov_b32_e32 v4, v1
	v_mov_b32_e32 v5, v1
	v_mov_b32_e32 v6, v1
	v_mov_b32_e32 v7, v1
	v_mov_b32_e32 v8, v1
	v_mov_b32_e32 v9, v1
	v_mov_b32_e32 v10, v1
	v_mov_b32_e32 v11, v1
	v_mov_b32_e32 v12, v1
	v_mov_b32_e32 v13, v1
	v_mov_b64_e32 v[30:31], v[14:15]
	v_mov_b64_e32 v[46:47], v[14:15]
	v_mov_b64_e32 v[62:63], v[14:15]
	v_mov_b64_e32 v[78:79], v[14:15]
	s_mov_b32 s34, 1
	s_add_i32 s35, s35, 64
	s_add_i32 s38, s38, 64
	s_mov_b32 s39, 0
	v_mov_b32_e32 v130, 0
	v_mov_b32_e32 v129, 0xf149f2ca
	v_mov_b64_e32 v[28:29], v[12:13]
	v_mov_b64_e32 v[26:27], v[10:11]
	v_mov_b64_e32 v[24:25], v[8:9]
	v_mov_b64_e32 v[22:23], v[6:7]
	v_mov_b64_e32 v[20:21], v[4:5]
	v_mov_b64_e32 v[18:19], v[2:3]
	v_mov_b64_e32 v[16:17], v[0:1]
	v_mov_b64_e32 v[44:45], v[12:13]
	v_mov_b64_e32 v[42:43], v[10:11]
	v_mov_b64_e32 v[40:41], v[8:9]
	v_mov_b64_e32 v[38:39], v[6:7]
	v_mov_b64_e32 v[36:37], v[4:5]
	v_mov_b64_e32 v[34:35], v[2:3]
	v_mov_b64_e32 v[32:33], v[0:1]
	v_mov_b64_e32 v[60:61], v[12:13]
	v_mov_b64_e32 v[58:59], v[10:11]
	v_mov_b64_e32 v[56:57], v[8:9]
	v_mov_b64_e32 v[54:55], v[6:7]
	v_mov_b64_e32 v[52:53], v[4:5]
	v_mov_b64_e32 v[50:51], v[2:3]
	v_mov_b64_e32 v[48:49], v[0:1]
	v_mov_b64_e32 v[76:77], v[12:13]
	v_mov_b64_e32 v[74:75], v[10:11]
	v_mov_b64_e32 v[72:73], v[8:9]
	v_mov_b64_e32 v[70:71], v[6:7]
	v_mov_b64_e32 v[68:69], v[4:5]
	v_mov_b64_e32 v[66:67], v[2:3]
	v_mov_b64_e32 v[64:65], v[0:1]
	s_waitcnt vmcnt(0) lgkmcnt(0)
	s_barrier
	s_add_i32 s2, s34, -1
	s_and_b32 s40, s2, 1
	s_cmp_ge_u32 s34, s59
	s_cbranch_scc1 .LBB0_600
